# LRU in-chunk scans on row pairs (ds_read2_b32/ds_write2_b32): half the LDS ops so the lgkmcnt window covers twice the lookahead
# speedup vs baseline: 1.1877x; 1.0033x over previous
.LBB0_988:
	v_mov_b32_e32 v221, v130
	v_add_u32_e32 v222, 0x6400, v130
	ds_read2_b32 v[224:225], v221 offset1:100
	ds_read2_b32 v[226:227], v222 offset1:100
	v_add_u32_e32 v221, 0x320, v221
	v_add_u32_e32 v222, 0x320, v222
	ds_read2_b32 v[228:229], v221 offset1:100
	ds_read2_b32 v[230:231], v222 offset1:100
	v_add_u32_e32 v221, 0x320, v221
	v_add_u32_e32 v222, 0x320, v222
	ds_read2_b32 v[232:233], v221 offset1:100
	ds_read2_b32 v[234:235], v222 offset1:100
	v_add_u32_e32 v221, 0x320, v221
	v_add_u32_e32 v222, 0x320, v222
	ds_read2_b32 v[236:237], v221 offset1:100
	ds_read2_b32 v[238:239], v222 offset1:100
	v_add_u32_e32 v221, 0x320, v221
	v_add_u32_e32 v222, 0x320, v222
	ds_read2_b32 v[240:241], v221 offset1:100
	ds_read2_b32 v[242:243], v222 offset1:100
	v_add_u32_e32 v221, 0x320, v221
	v_add_u32_e32 v222, 0x320, v222
	ds_read2_b32 v[244:245], v221 offset1:100
	ds_read2_b32 v[246:247], v222 offset1:100
	v_add_u32_e32 v221, 0x320, v221
	v_add_u32_e32 v222, 0x320, v222
	s_waitcnt lgkmcnt(10)
	v_fma_f32 v128, v128, v224, v226
	v_mul_f32_e32 v127, v127, v224
	v_fma_f32 v128, v128, v225, v227
	v_mul_f32_e32 v127, v127, v225
	ds_read2_b32 v[248:249], v221 offset1:100
	ds_read2_b32 v[250:251], v222 offset1:100
	v_add_u32_e32 v221, 0x320, v221
	v_add_u32_e32 v222, 0x320, v222
	s_waitcnt lgkmcnt(10)
	v_fma_f32 v128, v128, v228, v230
	v_mul_f32_e32 v127, v127, v228
	v_fma_f32 v128, v128, v229, v231
	v_mul_f32_e32 v127, v127, v229
	ds_read2_b32 v[224:225], v221 offset1:100
	ds_read2_b32 v[226:227], v222 offset1:100
	v_add_u32_e32 v221, 0x320, v221
	v_add_u32_e32 v222, 0x320, v222
	s_waitcnt lgkmcnt(10)
	v_fma_f32 v128, v128, v232, v234
	v_mul_f32_e32 v127, v127, v232
	v_fma_f32 v128, v128, v233, v235
	v_mul_f32_e32 v127, v127, v233
	ds_read2_b32 v[228:229], v221 offset1:100
	ds_read2_b32 v[230:231], v222 offset1:100
	v_add_u32_e32 v221, 0x320, v221
	v_add_u32_e32 v222, 0x320, v222
	s_waitcnt lgkmcnt(10)
	v_fma_f32 v128, v128, v236, v238
	v_mul_f32_e32 v127, v127, v236
	v_fma_f32 v128, v128, v237, v239
	v_mul_f32_e32 v127, v127, v237
	ds_read2_b32 v[232:233], v221 offset1:100
	ds_read2_b32 v[234:235], v222 offset1:100
	v_add_u32_e32 v221, 0x320, v221
	v_add_u32_e32 v222, 0x320, v222
	s_cmp_eq_u32 s50, 8
	s_cbranch_scc1 .Lscan_exit_A
	s_waitcnt lgkmcnt(10)
	v_fma_f32 v128, v128, v240, v242
	v_mul_f32_e32 v127, v127, v240
	v_fma_f32 v128, v128, v241, v243
	v_mul_f32_e32 v127, v127, v241
	ds_read2_b32 v[236:237], v221 offset1:100
	ds_read2_b32 v[238:239], v222 offset1:100
	v_add_u32_e32 v221, 0x320, v221
	v_add_u32_e32 v222, 0x320, v222
	s_waitcnt lgkmcnt(10)
	v_fma_f32 v128, v128, v244, v246
	v_mul_f32_e32 v127, v127, v244
	v_fma_f32 v128, v128, v245, v247
	v_mul_f32_e32 v127, v127, v245
	ds_read2_b32 v[240:241], v221 offset1:100
	ds_read2_b32 v[242:243], v222 offset1:100
	v_add_u32_e32 v221, 0x320, v221
	v_add_u32_e32 v222, 0x320, v222
	s_waitcnt lgkmcnt(10)
	v_fma_f32 v128, v128, v248, v250
	v_mul_f32_e32 v127, v127, v248
	v_fma_f32 v128, v128, v249, v251
	v_mul_f32_e32 v127, v127, v249
	ds_read2_b32 v[244:245], v221 offset1:100
	ds_read2_b32 v[246:247], v222 offset1:100
	v_add_u32_e32 v221, 0x320, v221
	v_add_u32_e32 v222, 0x320, v222
	s_waitcnt lgkmcnt(10)
	v_fma_f32 v128, v128, v224, v226
	v_mul_f32_e32 v127, v127, v224
	v_fma_f32 v128, v128, v225, v227
	v_mul_f32_e32 v127, v127, v225
	ds_read2_b32 v[248:249], v221 offset1:100
	ds_read2_b32 v[250:251], v222 offset1:100
	v_add_u32_e32 v221, 0x320, v221
	v_add_u32_e32 v222, 0x320, v222
	s_cmp_eq_u32 s50, 16
	s_cbranch_scc1 .Lscan_exit_A
	s_waitcnt lgkmcnt(10)
	v_fma_f32 v128, v128, v228, v230
	v_mul_f32_e32 v127, v127, v228
	v_fma_f32 v128, v128, v229, v231
	v_mul_f32_e32 v127, v127, v229
	ds_read2_b32 v[224:225], v221 offset1:100
	ds_read2_b32 v[226:227], v222 offset1:100
	v_add_u32_e32 v221, 0x320, v221
	v_add_u32_e32 v222, 0x320, v222
	s_waitcnt lgkmcnt(10)
	v_fma_f32 v128, v128, v232, v234
	v_mul_f32_e32 v127, v127, v232
	v_fma_f32 v128, v128, v233, v235
	v_mul_f32_e32 v127, v127, v233
	ds_read2_b32 v[228:229], v221 offset1:100
	ds_read2_b32 v[230:231], v222 offset1:100
	v_add_u32_e32 v221, 0x320, v221
	v_add_u32_e32 v222, 0x320, v222
	s_waitcnt lgkmcnt(10)
	v_fma_f32 v128, v128, v236, v238
	v_mul_f32_e32 v127, v127, v236
	v_fma_f32 v128, v128, v237, v239
	v_mul_f32_e32 v127, v127, v237
	ds_read2_b32 v[232:233], v221 offset1:100
	ds_read2_b32 v[234:235], v222 offset1:100
	v_add_u32_e32 v221, 0x320, v221
	v_add_u32_e32 v222, 0x320, v222
	s_waitcnt lgkmcnt(10)
	v_fma_f32 v128, v128, v240, v242
	v_mul_f32_e32 v127, v127, v240
	v_fma_f32 v128, v128, v241, v243
	v_mul_f32_e32 v127, v127, v241
	ds_read2_b32 v[236:237], v221 offset1:100
	ds_read2_b32 v[238:239], v222 offset1:100
	v_add_u32_e32 v221, 0x320, v221
	v_add_u32_e32 v222, 0x320, v222
	s_cmp_eq_u32 s50, 24
	s_cbranch_scc1 .Lscan_exit_A
	s_waitcnt lgkmcnt(10)
	v_fma_f32 v128, v128, v244, v246
	v_mul_f32_e32 v127, v127, v244
	v_fma_f32 v128, v128, v245, v247
	v_mul_f32_e32 v127, v127, v245
	ds_read2_b32 v[240:241], v221 offset1:100
	ds_read2_b32 v[242:243], v222 offset1:100
	v_add_u32_e32 v221, 0x320, v221
	v_add_u32_e32 v222, 0x320, v222
	s_waitcnt lgkmcnt(10)
	v_fma_f32 v128, v128, v248, v250
	v_mul_f32_e32 v127, v127, v248
	v_fma_f32 v128, v128, v249, v251
	v_mul_f32_e32 v127, v127, v249
	ds_read2_b32 v[244:245], v221 offset1:100
	ds_read2_b32 v[246:247], v222 offset1:100
	v_add_u32_e32 v221, 0x320, v221
	v_add_u32_e32 v222, 0x320, v222
	s_waitcnt lgkmcnt(10)
	v_fma_f32 v128, v128, v224, v226
	v_mul_f32_e32 v127, v127, v224
	v_fma_f32 v128, v128, v225, v227
	v_mul_f32_e32 v127, v127, v225
	ds_read2_b32 v[248:249], v221 offset1:100
	ds_read2_b32 v[250:251], v222 offset1:100
	v_add_u32_e32 v221, 0x320, v221
	v_add_u32_e32 v222, 0x320, v222
	s_waitcnt lgkmcnt(10)
	v_fma_f32 v128, v128, v228, v230
	v_mul_f32_e32 v127, v127, v228
	v_fma_f32 v128, v128, v229, v231
	v_mul_f32_e32 v127, v127, v229
	ds_read2_b32 v[224:225], v221 offset1:100
	ds_read2_b32 v[226:227], v222 offset1:100
	v_add_u32_e32 v221, 0x320, v221
	v_add_u32_e32 v222, 0x320, v222
	s_cmp_eq_u32 s50, 32
	s_cbranch_scc1 .Lscan_exit_A
	s_waitcnt lgkmcnt(10)
	v_fma_f32 v128, v128, v232, v234
	v_mul_f32_e32 v127, v127, v232
	v_fma_f32 v128, v128, v233, v235
	v_mul_f32_e32 v127, v127, v233
	ds_read2_b32 v[228:229], v221 offset1:100
	ds_read2_b32 v[230:231], v222 offset1:100
	v_add_u32_e32 v221, 0x320, v221
	v_add_u32_e32 v222, 0x320, v222
	s_waitcnt lgkmcnt(10)
	v_fma_f32 v128, v128, v236, v238
	v_mul_f32_e32 v127, v127, v236
	v_fma_f32 v128, v128, v237, v239
	v_mul_f32_e32 v127, v127, v237
	ds_read2_b32 v[232:233], v221 offset1:100
	ds_read2_b32 v[234:235], v222 offset1:100
	v_add_u32_e32 v221, 0x320, v221
	v_add_u32_e32 v222, 0x320, v222
	s_waitcnt lgkmcnt(10)
	v_fma_f32 v128, v128, v240, v242
	v_mul_f32_e32 v127, v127, v240
	v_fma_f32 v128, v128, v241, v243
	v_mul_f32_e32 v127, v127, v241
	ds_read2_b32 v[236:237], v221 offset1:100
	ds_read2_b32 v[238:239], v222 offset1:100
	v_add_u32_e32 v221, 0x320, v221
	v_add_u32_e32 v222, 0x320, v222
	s_waitcnt lgkmcnt(10)
	v_fma_f32 v128, v128, v244, v246
	v_mul_f32_e32 v127, v127, v244
	v_fma_f32 v128, v128, v245, v247
	v_mul_f32_e32 v127, v127, v245
	ds_read2_b32 v[240:241], v221 offset1:100
	ds_read2_b32 v[242:243], v222 offset1:100
	v_add_u32_e32 v221, 0x320, v221
	v_add_u32_e32 v222, 0x320, v222
	s_cmp_eq_u32 s50, 40
	s_cbranch_scc1 .Lscan_exit_A
	s_waitcnt lgkmcnt(10)
	v_fma_f32 v128, v128, v248, v250
	v_mul_f32_e32 v127, v127, v248
	v_fma_f32 v128, v128, v249, v251
	v_mul_f32_e32 v127, v127, v249
	ds_read2_b32 v[244:245], v221 offset1:100
	ds_read2_b32 v[246:247], v222 offset1:100
	v_add_u32_e32 v221, 0x320, v221
	v_add_u32_e32 v222, 0x320, v222
	s_waitcnt lgkmcnt(10)
	v_fma_f32 v128, v128, v224, v226
	v_mul_f32_e32 v127, v127, v224
	v_fma_f32 v128, v128, v225, v227
	v_mul_f32_e32 v127, v127, v225
	ds_read2_b32 v[248:249], v221 offset1:100
	ds_read2_b32 v[250:251], v222 offset1:100
	v_add_u32_e32 v221, 0x320, v221
	v_add_u32_e32 v222, 0x320, v222
	s_waitcnt lgkmcnt(10)
	v_fma_f32 v128, v128, v228, v230
	v_mul_f32_e32 v127, v127, v228
	v_fma_f32 v128, v128, v229, v231
	v_mul_f32_e32 v127, v127, v229
	ds_read2_b32 v[224:225], v221 offset1:100
	ds_read2_b32 v[226:227], v222 offset1:100
	v_add_u32_e32 v221, 0x320, v221
	v_add_u32_e32 v222, 0x320, v222
	s_waitcnt lgkmcnt(10)
	v_fma_f32 v128, v128, v232, v234
	v_mul_f32_e32 v127, v127, v232
	v_fma_f32 v128, v128, v233, v235
	v_mul_f32_e32 v127, v127, v233
	ds_read2_b32 v[228:229], v221 offset1:100
	ds_read2_b32 v[230:231], v222 offset1:100
	v_add_u32_e32 v221, 0x320, v221
	v_add_u32_e32 v222, 0x320, v222
	s_cmp_eq_u32 s50, 48
	s_cbranch_scc1 .Lscan_exit_A
	s_waitcnt lgkmcnt(10)
	v_fma_f32 v128, v128, v236, v238
	v_mul_f32_e32 v127, v127, v236
	v_fma_f32 v128, v128, v237, v239
	v_mul_f32_e32 v127, v127, v237
	ds_read2_b32 v[232:233], v221 offset1:100
	ds_read2_b32 v[234:235], v222 offset1:100
	v_add_u32_e32 v221, 0x320, v221
	v_add_u32_e32 v222, 0x320, v222
	s_waitcnt lgkmcnt(10)
	v_fma_f32 v128, v128, v240, v242
	v_mul_f32_e32 v127, v127, v240
	v_fma_f32 v128, v128, v241, v243
	v_mul_f32_e32 v127, v127, v241
	ds_read2_b32 v[236:237], v221 offset1:100
	ds_read2_b32 v[238:239], v222 offset1:100
	v_add_u32_e32 v221, 0x320, v221
	v_add_u32_e32 v222, 0x320, v222
	s_waitcnt lgkmcnt(10)
	v_fma_f32 v128, v128, v244, v246
	v_mul_f32_e32 v127, v127, v244
	v_fma_f32 v128, v128, v245, v247
	v_mul_f32_e32 v127, v127, v245
	s_waitcnt lgkmcnt(8)
	v_fma_f32 v128, v128, v248, v250
	v_mul_f32_e32 v127, v127, v248
	v_fma_f32 v128, v128, v249, v251
	v_mul_f32_e32 v127, v127, v249
	s_cmp_eq_u32 s50, 56
	s_cbranch_scc1 .Lscan_exit_A
	s_waitcnt lgkmcnt(6)
	v_fma_f32 v128, v128, v224, v226
	v_mul_f32_e32 v127, v127, v224
	v_fma_f32 v128, v128, v225, v227
	v_mul_f32_e32 v127, v127, v225
	s_waitcnt lgkmcnt(4)
	v_fma_f32 v128, v128, v228, v230
	v_mul_f32_e32 v127, v127, v228
	v_fma_f32 v128, v128, v229, v231
	v_mul_f32_e32 v127, v127, v229
	s_waitcnt lgkmcnt(2)
	v_fma_f32 v128, v128, v232, v234
	v_mul_f32_e32 v127, v127, v232
	v_fma_f32 v128, v128, v233, v235
	v_mul_f32_e32 v127, v127, v233
	s_waitcnt lgkmcnt(0)
	v_fma_f32 v128, v128, v236, v238
	v_mul_f32_e32 v127, v127, v236
	v_fma_f32 v128, v128, v237, v239
	v_mul_f32_e32 v127, v127, v237

.LBB0_1212:
	v_mov_b32_e32 v139, v138
	v_add_u32_e32 v140, 0x6400, v138
	v_add_u32_e32 v141, 0x6400, v138
	ds_read2_b32 v[226:227], v139 offset1:100
	ds_read2_b32 v[228:229], v140 offset1:100
	v_add_u32_e32 v139, 0x320, v139
	v_add_u32_e32 v140, 0x320, v140
	ds_read2_b32 v[230:231], v139 offset1:100
	ds_read2_b32 v[232:233], v140 offset1:100
	v_add_u32_e32 v139, 0x320, v139
	v_add_u32_e32 v140, 0x320, v140
	ds_read2_b32 v[234:235], v139 offset1:100
	ds_read2_b32 v[236:237], v140 offset1:100
	v_add_u32_e32 v139, 0x320, v139
	v_add_u32_e32 v140, 0x320, v140
	ds_read2_b32 v[238:239], v139 offset1:100
	ds_read2_b32 v[240:241], v140 offset1:100
	v_add_u32_e32 v139, 0x320, v139
	v_add_u32_e32 v140, 0x320, v140
	s_waitcnt lgkmcnt(6)
	v_fma_f32 v228, v175, v226, v228
	v_fma_f32 v229, v228, v227, v229
	ds_write2_b32 v141, v228, v229 offset1:100
	v_add_u32_e32 v141, 0x320, v141
	ds_read2_b32 v[242:243], v139 offset1:100
	ds_read2_b32 v[244:245], v140 offset1:100
	v_add_u32_e32 v139, 0x320, v139
	v_add_u32_e32 v140, 0x320, v140
	s_waitcnt lgkmcnt(7)
	v_fma_f32 v232, v229, v230, v232
	v_fma_f32 v233, v232, v231, v233
	ds_write2_b32 v141, v232, v233 offset1:100
	v_add_u32_e32 v141, 0x320, v141
	ds_read2_b32 v[226:227], v139 offset1:100
	ds_read2_b32 v[228:229], v140 offset1:100
	v_add_u32_e32 v139, 0x320, v139
	v_add_u32_e32 v140, 0x320, v140
	s_waitcnt lgkmcnt(8)
	v_fma_f32 v236, v233, v234, v236
	v_fma_f32 v237, v236, v235, v237
	ds_write2_b32 v141, v236, v237 offset1:100
	v_add_u32_e32 v141, 0x320, v141
	ds_read2_b32 v[230:231], v139 offset1:100
	ds_read2_b32 v[232:233], v140 offset1:100
	v_add_u32_e32 v139, 0x320, v139
	v_add_u32_e32 v140, 0x320, v140
	s_waitcnt lgkmcnt(9)
	v_fma_f32 v240, v237, v238, v240
	v_fma_f32 v241, v240, v239, v241
	ds_write2_b32 v141, v240, v241 offset1:100
	v_add_u32_e32 v141, 0x320, v141
	ds_read2_b32 v[234:235], v139 offset1:100
	ds_read2_b32 v[236:237], v140 offset1:100
	v_add_u32_e32 v139, 0x320, v139
	v_add_u32_e32 v140, 0x320, v140
	v_mov_b32_e32 v175, v241
	s_cmp_eq_u32 s72, 8
	s_cbranch_scc1 .Lscan_exit_B
	s_waitcnt lgkmcnt(9)
	v_fma_f32 v244, v241, v242, v244
	v_fma_f32 v245, v244, v243, v245
	ds_write2_b32 v141, v244, v245 offset1:100
	v_add_u32_e32 v141, 0x320, v141
	ds_read2_b32 v[238:239], v139 offset1:100
	ds_read2_b32 v[240:241], v140 offset1:100
	v_add_u32_e32 v139, 0x320, v139
	v_add_u32_e32 v140, 0x320, v140
	s_waitcnt lgkmcnt(9)
	v_fma_f32 v228, v245, v226, v228
	v_fma_f32 v229, v228, v227, v229
	ds_write2_b32 v141, v228, v229 offset1:100
	v_add_u32_e32 v141, 0x320, v141
	ds_read2_b32 v[242:243], v139 offset1:100
	ds_read2_b32 v[244:245], v140 offset1:100
	v_add_u32_e32 v139, 0x320, v139
	v_add_u32_e32 v140, 0x320, v140
	s_waitcnt lgkmcnt(9)
	v_fma_f32 v232, v229, v230, v232
	v_fma_f32 v233, v232, v231, v233
	ds_write2_b32 v141, v232, v233 offset1:100
	v_add_u32_e32 v141, 0x320, v141
	ds_read2_b32 v[226:227], v139 offset1:100
	ds_read2_b32 v[228:229], v140 offset1:100
	v_add_u32_e32 v139, 0x320, v139
	v_add_u32_e32 v140, 0x320, v140
	s_waitcnt lgkmcnt(9)
	v_fma_f32 v236, v233, v234, v236
	v_fma_f32 v237, v236, v235, v237
	ds_write2_b32 v141, v236, v237 offset1:100
	v_add_u32_e32 v141, 0x320, v141
	ds_read2_b32 v[230:231], v139 offset1:100
	ds_read2_b32 v[232:233], v140 offset1:100
	v_add_u32_e32 v139, 0x320, v139
	v_add_u32_e32 v140, 0x320, v140
	v_mov_b32_e32 v175, v237
	s_cmp_eq_u32 s72, 16
	s_cbranch_scc1 .Lscan_exit_B
	s_waitcnt lgkmcnt(9)
	v_fma_f32 v240, v237, v238, v240
	v_fma_f32 v241, v240, v239, v241
	ds_write2_b32 v141, v240, v241 offset1:100
	v_add_u32_e32 v141, 0x320, v141
	ds_read2_b32 v[234:235], v139 offset1:100
	ds_read2_b32 v[236:237], v140 offset1:100
	v_add_u32_e32 v139, 0x320, v139
	v_add_u32_e32 v140, 0x320, v140
	s_waitcnt lgkmcnt(9)
	v_fma_f32 v244, v241, v242, v244
	v_fma_f32 v245, v244, v243, v245
	ds_write2_b32 v141, v244, v245 offset1:100
	v_add_u32_e32 v141, 0x320, v141
	ds_read2_b32 v[238:239], v139 offset1:100
	ds_read2_b32 v[240:241], v140 offset1:100
	v_add_u32_e32 v139, 0x320, v139
	v_add_u32_e32 v140, 0x320, v140
	s_waitcnt lgkmcnt(9)
	v_fma_f32 v228, v245, v226, v228
	v_fma_f32 v229, v228, v227, v229
	ds_write2_b32 v141, v228, v229 offset1:100
	v_add_u32_e32 v141, 0x320, v141
	ds_read2_b32 v[242:243], v139 offset1:100
	ds_read2_b32 v[244:245], v140 offset1:100
	v_add_u32_e32 v139, 0x320, v139
	v_add_u32_e32 v140, 0x320, v140
	s_waitcnt lgkmcnt(9)
	v_fma_f32 v232, v229, v230, v232
	v_fma_f32 v233, v232, v231, v233
	ds_write2_b32 v141, v232, v233 offset1:100
	v_add_u32_e32 v141, 0x320, v141
	ds_read2_b32 v[226:227], v139 offset1:100
	ds_read2_b32 v[228:229], v140 offset1:100
	v_add_u32_e32 v139, 0x320, v139
	v_add_u32_e32 v140, 0x320, v140
	v_mov_b32_e32 v175, v233
	s_cmp_eq_u32 s72, 24
	s_cbranch_scc1 .Lscan_exit_B
	s_waitcnt lgkmcnt(9)
	v_fma_f32 v236, v233, v234, v236
	v_fma_f32 v237, v236, v235, v237
	ds_write2_b32 v141, v236, v237 offset1:100
	v_add_u32_e32 v141, 0x320, v141
	ds_read2_b32 v[230:231], v139 offset1:100
	ds_read2_b32 v[232:233], v140 offset1:100
	v_add_u32_e32 v139, 0x320, v139
	v_add_u32_e32 v140, 0x320, v140
	s_waitcnt lgkmcnt(9)
	v_fma_f32 v240, v237, v238, v240
	v_fma_f32 v241, v240, v239, v241
	ds_write2_b32 v141, v240, v241 offset1:100
	v_add_u32_e32 v141, 0x320, v141
	ds_read2_b32 v[234:235], v139 offset1:100
	ds_read2_b32 v[236:237], v140 offset1:100
	v_add_u32_e32 v139, 0x320, v139
	v_add_u32_e32 v140, 0x320, v140
	s_waitcnt lgkmcnt(9)
	v_fma_f32 v244, v241, v242, v244
	v_fma_f32 v245, v244, v243, v245
	ds_write2_b32 v141, v244, v245 offset1:100
	v_add_u32_e32 v141, 0x320, v141
	ds_read2_b32 v[238:239], v139 offset1:100
	ds_read2_b32 v[240:241], v140 offset1:100
	v_add_u32_e32 v139, 0x320, v139
	v_add_u32_e32 v140, 0x320, v140
	s_waitcnt lgkmcnt(9)
	v_fma_f32 v228, v245, v226, v228
	v_fma_f32 v229, v228, v227, v229
	ds_write2_b32 v141, v228, v229 offset1:100
	v_add_u32_e32 v141, 0x320, v141
	ds_read2_b32 v[242:243], v139 offset1:100
	ds_read2_b32 v[244:245], v140 offset1:100
	v_add_u32_e32 v139, 0x320, v139
	v_add_u32_e32 v140, 0x320, v140
	v_mov_b32_e32 v175, v229
	s_cmp_eq_u32 s72, 32
	s_cbranch_scc1 .Lscan_exit_B
	s_waitcnt lgkmcnt(9)
	v_fma_f32 v232, v229, v230, v232
	v_fma_f32 v233, v232, v231, v233
	ds_write2_b32 v141, v232, v233 offset1:100
	v_add_u32_e32 v141, 0x320, v141
	ds_read2_b32 v[226:227], v139 offset1:100
	ds_read2_b32 v[228:229], v140 offset1:100
	v_add_u32_e32 v139, 0x320, v139
	v_add_u32_e32 v140, 0x320, v140
	s_waitcnt lgkmcnt(9)
	v_fma_f32 v236, v233, v234, v236
	v_fma_f32 v237, v236, v235, v237
	ds_write2_b32 v141, v236, v237 offset1:100
	v_add_u32_e32 v141, 0x320, v141
	ds_read2_b32 v[230:231], v139 offset1:100
	ds_read2_b32 v[232:233], v140 offset1:100
	v_add_u32_e32 v139, 0x320, v139
	v_add_u32_e32 v140, 0x320, v140
	s_waitcnt lgkmcnt(9)
	v_fma_f32 v240, v237, v238, v240
	v_fma_f32 v241, v240, v239, v241
	ds_write2_b32 v141, v240, v241 offset1:100
	v_add_u32_e32 v141, 0x320, v141
	ds_read2_b32 v[234:235], v139 offset1:100
	ds_read2_b32 v[236:237], v140 offset1:100
	v_add_u32_e32 v139, 0x320, v139
	v_add_u32_e32 v140, 0x320, v140
	s_waitcnt lgkmcnt(9)
	v_fma_f32 v244, v241, v242, v244
	v_fma_f32 v245, v244, v243, v245
	ds_write2_b32 v141, v244, v245 offset1:100
	v_add_u32_e32 v141, 0x320, v141
	ds_read2_b32 v[238:239], v139 offset1:100
	ds_read2_b32 v[240:241], v140 offset1:100
	v_add_u32_e32 v139, 0x320, v139
	v_add_u32_e32 v140, 0x320, v140
	v_mov_b32_e32 v175, v245
	s_cmp_eq_u32 s72, 40
	s_cbranch_scc1 .Lscan_exit_B
	s_waitcnt lgkmcnt(9)
	v_fma_f32 v228, v245, v226, v228
	v_fma_f32 v229, v228, v227, v229
	ds_write2_b32 v141, v228, v229 offset1:100
	v_add_u32_e32 v141, 0x320, v141
	ds_read2_b32 v[242:243], v139 offset1:100
	ds_read2_b32 v[244:245], v140 offset1:100
	v_add_u32_e32 v139, 0x320, v139
	v_add_u32_e32 v140, 0x320, v140
	s_waitcnt lgkmcnt(9)
	v_fma_f32 v232, v229, v230, v232
	v_fma_f32 v233, v232, v231, v233
	ds_write2_b32 v141, v232, v233 offset1:100
	v_add_u32_e32 v141, 0x320, v141
	ds_read2_b32 v[226:227], v139 offset1:100
	ds_read2_b32 v[228:229], v140 offset1:100
	v_add_u32_e32 v139, 0x320, v139
	v_add_u32_e32 v140, 0x320, v140
	s_waitcnt lgkmcnt(9)
	v_fma_f32 v236, v233, v234, v236
	v_fma_f32 v237, v236, v235, v237
	ds_write2_b32 v141, v236, v237 offset1:100
	v_add_u32_e32 v141, 0x320, v141
	ds_read2_b32 v[230:231], v139 offset1:100
	ds_read2_b32 v[232:233], v140 offset1:100
	v_add_u32_e32 v139, 0x320, v139
	v_add_u32_e32 v140, 0x320, v140
	s_waitcnt lgkmcnt(9)
	v_fma_f32 v240, v237, v238, v240
	v_fma_f32 v241, v240, v239, v241
	ds_write2_b32 v141, v240, v241 offset1:100
	v_add_u32_e32 v141, 0x320, v141
	ds_read2_b32 v[234:235], v139 offset1:100
	ds_read2_b32 v[236:237], v140 offset1:100
	v_add_u32_e32 v139, 0x320, v139
	v_add_u32_e32 v140, 0x320, v140
	v_mov_b32_e32 v175, v241
	s_cmp_eq_u32 s72, 48
	s_cbranch_scc1 .Lscan_exit_B
	s_waitcnt lgkmcnt(9)
	v_fma_f32 v244, v241, v242, v244
	v_fma_f32 v245, v244, v243, v245
	ds_write2_b32 v141, v244, v245 offset1:100
	v_add_u32_e32 v141, 0x320, v141
	ds_read2_b32 v[238:239], v139 offset1:100
	ds_read2_b32 v[240:241], v140 offset1:100
	v_add_u32_e32 v139, 0x320, v139
	v_add_u32_e32 v140, 0x320, v140
	s_waitcnt lgkmcnt(9)
	v_fma_f32 v228, v245, v226, v228
	v_fma_f32 v229, v228, v227, v229
	ds_write2_b32 v141, v228, v229 offset1:100
	v_add_u32_e32 v141, 0x320, v141
	ds_read2_b32 v[242:243], v139 offset1:100
	ds_read2_b32 v[244:245], v140 offset1:100
	v_add_u32_e32 v139, 0x320, v139
	v_add_u32_e32 v140, 0x320, v140
	s_waitcnt lgkmcnt(9)
	v_fma_f32 v232, v229, v230, v232
	v_fma_f32 v233, v232, v231, v233
	ds_write2_b32 v141, v232, v233 offset1:100
	v_add_u32_e32 v141, 0x320, v141
	ds_read2_b32 v[226:227], v139 offset1:100
	ds_read2_b32 v[228:229], v140 offset1:100
	v_add_u32_e32 v139, 0x320, v139
	v_add_u32_e32 v140, 0x320, v140
	s_waitcnt lgkmcnt(9)
	v_fma_f32 v236, v233, v234, v236
	v_fma_f32 v237, v236, v235, v237
	ds_write2_b32 v141, v236, v237 offset1:100
	v_add_u32_e32 v141, 0x320, v141
	ds_read2_b32 v[230:231], v139 offset1:100
	ds_read2_b32 v[232:233], v140 offset1:100
	v_add_u32_e32 v139, 0x320, v139
	v_add_u32_e32 v140, 0x320, v140
	v_mov_b32_e32 v175, v237
	s_cmp_eq_u32 s72, 56
	s_cbranch_scc1 .Lscan_exit_B
	s_waitcnt lgkmcnt(9)
	v_fma_f32 v240, v237, v238, v240
	v_fma_f32 v241, v240, v239, v241
	ds_write2_b32 v141, v240, v241 offset1:100
	v_add_u32_e32 v141, 0x320, v141
	s_waitcnt lgkmcnt(7)
	v_fma_f32 v244, v241, v242, v244
	v_fma_f32 v245, v244, v243, v245
	ds_write2_b32 v141, v244, v245 offset1:100
	v_add_u32_e32 v141, 0x320, v141
	s_waitcnt lgkmcnt(5)
	v_fma_f32 v228, v245, v226, v228
	v_fma_f32 v229, v228, v227, v229
	ds_write2_b32 v141, v228, v229 offset1:100
	v_add_u32_e32 v141, 0x320, v141
	s_waitcnt lgkmcnt(3)
	v_fma_f32 v232, v229, v230, v232
	v_fma_f32 v233, v232, v231, v233
	ds_write2_b32 v141, v232, v233 offset1:100
	v_add_u32_e32 v141, 0x320, v141
	v_mov_b32_e32 v175, v233
